# speedup vs baseline: 1.0109x; 1.0037x over previous
; #define MFMA(a, b, c) __builtin_amdgcn_mfma_f32_32x32x16_bf16((a), (b), (c), 0, 0, 0)
; template <bool SWAP, int MI>
; DI void gemm_main(const bf16_t* __restrict__ A, int lda, const bf16_t* __restrict__ B, int ldb, int K, char* smem, f32x16 (&acc)[MI][2]) {
;     ...
;     for (int k0 = 0; k0 < K; k0 += 64) {
;         const bool more = (k0 + 64) < K;
;         if (more) {
; #pragma unroll
;             for (int i = 0; i < 2 * MI; ++i) ra[i] = *(const u32x4*)(ap + (size_t)(32 * i) * lda + k0 + 64);
; #pragma unroll
;             for (int i = 0; i < 4; ++i) rb[i] = *(const u32x4*)(bp + (size_t)(32 * i) * ldb + k0 + 64);
;         }
; #pragma unroll
;         for (int s = 0; s < 4; ++s) {
;             bf16x8 af[MI], bfr[2];
; #pragma unroll
;             for (int i = 0; i < MI; ++i) af[i] = *(const bf16x8*)(sA + (wm * (MI * 32) + i * 32 + l31) * GLD + s * 16 + h * 8);
; #pragma unroll
;             for (int j = 0; j < 2; ++j) bfr[j] = *(const bf16x8*)(sB + (wn * 64 + j * 32 + l31) * GLD + s * 16 + h * 8);
; #pragma unroll
;             for (int i = 0; i < MI; ++i)
; #pragma unroll
;                 for (int j = 0; j < 2; ++j) {
;                     if (SWAP) acc[i][j] = MFMA(bfr[j], af[i], acc[i][j]);
;                     else acc[i][j] = MFMA(af[i], bfr[j], acc[i][j]);
;                 }
;         }
;         __syncthreads();
;         if (more) {
; #pragma unroll
;             for (int i = 0; i < 2 * MI; ++i) *(u32x4*)(sA + (lr + 32 * i) * GLD + lc) = ra[i];
; #pragma unroll
;             for (int i = 0; i < 4; ++i) *(u32x4*)(sB + (lr + 32 * i) * GLD + lc) = rb[i];
;         }
;         __syncthreads();
.LBB0_677:
	ds_read_b128 v[190:193], v189 offset:36864
	ds_read_b128 v[226:229], v187
	ds_read_b128 v[230:233], v189 offset:41472
	ds_read_b128 v[234:237], v187 offset:4608
	ds_read_b128 v[238:241], v187 offset:9216
	ds_read_b128 v[222:225], v188
	ds_read_b128 v[218:221], v189 offset:36896
	ds_read_b128 v[214:217], v189 offset:41504
	s_cmpk_lt_u32 s9, 0x3c0
	s_cselect_b64 s[12:13], -1, 0
	s_cmpk_gt_u32 s9, 0x3bf
	s_cselect_b64 s[10:11], -1, 0
	s_and_b64 vcc, exec, s[10:11]
	s_cbranch_vccnz .LBB0_679
	s_waitcnt vmcnt(5)
	v_lshl_add_u64 v[154:155], v[180:181], 0, v[0:1]
	v_add_co_u32_e32 v130, vcc, 0x4000000, v154
	s_waitcnt vmcnt(1)
	v_lshl_add_u64 v[170:171], v[182:183], 0, v[0:1]
	v_addc_co_u32_e32 v131, vcc, 0, v155, vcc
	v_add_co_u32_e32 v134, vcc, 0x4010000, v154
	s_nop 1
	v_addc_co_u32_e32 v135, vcc, 0, v155, vcc
	v_add_co_u32_e32 v138, vcc, 0x4020000, v154
	global_load_dwordx4 v[130:133], v[130:131], off offset:128
	s_nop 0
	global_load_dwordx4 v[134:137], v[134:135], off offset:128
	v_addc_co_u32_e32 v139, vcc, 0, v155, vcc
	v_add_co_u32_e32 v142, vcc, 0x4030000, v154
	s_nop 1
	v_addc_co_u32_e32 v143, vcc, 0, v155, vcc
	v_add_co_u32_e32 v146, vcc, 0x4040000, v154
	global_load_dwordx4 v[138:141], v[138:139], off offset:128
	s_nop 0
	global_load_dwordx4 v[142:145], v[142:143], off offset:128
	v_addc_co_u32_e32 v147, vcc, 0, v155, vcc
	v_add_co_u32_e32 v150, vcc, 0x4050000, v154
	s_nop 1
	v_addc_co_u32_e32 v151, vcc, 0, v155, vcc
	v_add_co_u32_e32 v156, vcc, 0x4060000, v154
	global_load_dwordx4 v[146:149], v[146:147], off offset:128
	s_nop 0
	global_load_dwordx4 v[150:153], v[150:151], off offset:128
	v_addc_co_u32_e32 v157, vcc, 0, v155, vcc
	v_add_co_u32_e32 v158, vcc, 0x4070000, v154
	s_nop 1
	v_addc_co_u32_e32 v159, vcc, 0, v155, vcc
	v_add_co_u32_e32 v162, vcc, s24, v170
	global_load_dwordx4 v[154:157], v[156:157], off offset:128
	s_nop 0
	global_load_dwordx4 v[158:161], v[158:159], off offset:128
	v_addc_co_u32_e32 v163, vcc, 0, v171, vcc
	v_add_co_u32_e32 v166, vcc, 0x18000, v170
	s_nop 1
	v_addc_co_u32_e32 v167, vcc, 0, v171, vcc
	v_add_co_u32_e32 v172, vcc, 0x28000, v170
	global_load_dwordx4 v[162:165], v[162:163], off offset:128
	s_nop 0
	global_load_dwordx4 v[166:169], v[166:167], off offset:128
	v_addc_co_u32_e32 v173, vcc, 0, v171, vcc
	s_waitcnt vmcnt(10)
	v_add_co_u32_e32 v174, vcc, 0x38000, v170
	s_nop 1
	v_addc_co_u32_e32 v175, vcc, 0, v171, vcc
	global_load_dwordx4 v[170:173], v[172:173], off offset:128
	s_nop 0
	global_load_dwordx4 v[174:177], v[174:175], off offset:128
.LBB0_679:
	s_andn2_b64 vcc, exec, s[12:13]
	s_waitcnt lgkmcnt(6)
	v_mfma_f32_32x32x16_bf16 v[114:129], v[190:193], v[226:229], v[114:129]
	s_waitcnt lgkmcnt(5)
	v_mfma_f32_32x32x16_bf16 v[98:113], v[230:233], v[226:229], v[98:113]
	ds_read_b128 v[226:229], v187 offset:32
	s_waitcnt lgkmcnt(5)
	v_mfma_f32_32x32x16_bf16 v[82:97], v[190:193], v[234:237], v[82:97]
	v_mfma_f32_32x32x16_bf16 v[66:81], v[230:233], v[234:237], v[66:81]
	ds_read_b128 v[234:237], v187 offset:4640
	s_waitcnt lgkmcnt(5)
	v_mfma_f32_32x32x16_bf16 v[50:65], v[190:193], v[238:241], v[50:65]
	v_mfma_f32_32x32x16_bf16 v[34:49], v[230:233], v[238:241], v[34:49]
	ds_read_b128 v[238:241], v187 offset:9248
	s_waitcnt lgkmcnt(5)
	v_mfma_f32_32x32x16_bf16 v[18:33], v[190:193], v[222:225], v[18:33]
	v_mfma_f32_32x32x16_bf16 v[2:17], v[230:233], v[222:225], v[2:17]
	ds_read_b128 v[222:225], v188 offset:32
	ds_read_b128 v[190:193], v189 offset:36928
	ds_read_b128 v[230:233], v189 offset:41536
	s_waitcnt lgkmcnt(5)
	v_mfma_f32_32x32x16_bf16 v[114:129], v[218:221], v[226:229], v[114:129]
	v_mfma_f32_32x32x16_bf16 v[98:113], v[214:217], v[226:229], v[98:113]
	ds_read_b128 v[226:229], v187 offset:64
	s_waitcnt lgkmcnt(5)
	v_mfma_f32_32x32x16_bf16 v[82:97], v[218:221], v[234:237], v[82:97]
	v_mfma_f32_32x32x16_bf16 v[66:81], v[214:217], v[234:237], v[66:81]
	ds_read_b128 v[234:237], v187 offset:4672
	s_waitcnt lgkmcnt(5)
	v_mfma_f32_32x32x16_bf16 v[50:65], v[218:221], v[238:241], v[50:65]
	v_mfma_f32_32x32x16_bf16 v[34:49], v[214:217], v[238:241], v[34:49]
	ds_read_b128 v[238:241], v187 offset:9280
	s_waitcnt lgkmcnt(5)
	v_mfma_f32_32x32x16_bf16 v[18:33], v[218:221], v[222:225], v[18:33]
	v_mfma_f32_32x32x16_bf16 v[2:17], v[214:217], v[222:225], v[2:17]
	ds_read_b128 v[222:225], v188 offset:64
	ds_read_b128 v[218:221], v189 offset:36960
	ds_read_b128 v[214:217], v189 offset:41568
	s_waitcnt lgkmcnt(5)
	v_mfma_f32_32x32x16_bf16 v[114:129], v[190:193], v[226:229], v[114:129]
	v_mfma_f32_32x32x16_bf16 v[98:113], v[230:233], v[226:229], v[98:113]
	ds_read_b128 v[226:229], v187 offset:96
	s_waitcnt lgkmcnt(5)
	v_mfma_f32_32x32x16_bf16 v[82:97], v[190:193], v[234:237], v[82:97]
	v_mfma_f32_32x32x16_bf16 v[66:81], v[230:233], v[234:237], v[66:81]
	ds_read_b128 v[234:237], v187 offset:4704
	s_waitcnt lgkmcnt(5)
	v_mfma_f32_32x32x16_bf16 v[50:65], v[190:193], v[238:241], v[50:65]
	v_mfma_f32_32x32x16_bf16 v[34:49], v[230:233], v[238:241], v[34:49]
	ds_read_b128 v[238:241], v187 offset:9312
	s_waitcnt lgkmcnt(5)
	v_mfma_f32_32x32x16_bf16 v[18:33], v[190:193], v[222:225], v[18:33]
	v_mfma_f32_32x32x16_bf16 v[2:17], v[230:233], v[222:225], v[2:17]
	ds_read_b128 v[222:225], v188 offset:96
	s_waitcnt lgkmcnt(3)
	v_mfma_f32_32x32x16_bf16 v[114:129], v[218:221], v[226:229], v[114:129]
	v_mfma_f32_32x32x16_bf16 v[98:113], v[214:217], v[226:229], v[98:113]
	s_waitcnt lgkmcnt(2)
	v_mfma_f32_32x32x16_bf16 v[82:97], v[218:221], v[234:237], v[82:97]
	v_mfma_f32_32x32x16_bf16 v[66:81], v[214:217], v[234:237], v[66:81]
	s_waitcnt lgkmcnt(0)
	s_barrier
	v_mfma_f32_32x32x16_bf16 v[50:65], v[218:221], v[238:241], v[50:65]
	v_mfma_f32_32x32x16_bf16 v[34:49], v[214:217], v[238:241], v[34:49]
	v_mfma_f32_32x32x16_bf16 v[18:33], v[218:221], v[222:225], v[18:33]
	v_mfma_f32_32x32x16_bf16 v[2:17], v[214:217], v[222:225], v[2:17]
	s_cbranch_vccnz .LBB0_676
	s_waitcnt vmcnt(11)
	ds_write_b128 v186, v[130:133]
	s_waitcnt vmcnt(10)
	ds_write_b128 v186, v[134:137] offset:4608
	s_waitcnt vmcnt(9)
	ds_write_b128 v186, v[138:141] offset:9216
	s_waitcnt vmcnt(8)
	ds_write_b128 v186, v[142:145] offset:13824
	s_waitcnt vmcnt(7)
	ds_write_b128 v186, v[146:149] offset:18432
	s_waitcnt vmcnt(6)
	ds_write_b128 v186, v[150:153] offset:23040
	s_waitcnt vmcnt(5)
	ds_write_b128 v186, v[154:157] offset:27648
	s_waitcnt vmcnt(4)
	ds_write_b128 v186, v[158:161] offset:32256
	s_waitcnt vmcnt(3)
	ds_write_b128 v186, v[162:165] offset:36864
	s_waitcnt vmcnt(2)
	ds_write_b128 v186, v[166:169] offset:41472
	s_waitcnt vmcnt(1)
	ds_write_b128 v186, v[170:173] offset:46080
	s_waitcnt vmcnt(0)
	ds_write_b128 v186, v[174:177] offset:50688
	s_branch .LBB0_676

; #define MFMA(a, b, c) __builtin_amdgcn_mfma_f32_32x32x16_bf16((a), (b), (c), 0, 0, 0)
; template <bool SWAP, int MI>
; DI void gemm_main(const bf16_t* __restrict__ A, int lda, const bf16_t* __restrict__ B, int ldb, int K, char* smem, f32x16 (&acc)[MI][2]) {
;     ...
;     for (int k0 = 0; k0 < K; k0 += 64) {
;         const bool more = (k0 + 64) < K;
;         if (more) {
; #pragma unroll
;             for (int i = 0; i < 2 * MI; ++i) ra[i] = *(const u32x4*)(ap + (size_t)(32 * i) * lda + k0 + 64);
; #pragma unroll
;             for (int i = 0; i < 4; ++i) rb[i] = *(const u32x4*)(bp + (size_t)(32 * i) * ldb + k0 + 64);
;         }
; #pragma unroll
;         for (int s = 0; s < 4; ++s) {
;             bf16x8 af[MI], bfr[2];
; #pragma unroll
;             for (int i = 0; i < MI; ++i) af[i] = *(const bf16x8*)(sA + (wm * (MI * 32) + i * 32 + l31) * GLD + s * 16 + h * 8);
; #pragma unroll
;             for (int j = 0; j < 2; ++j) bfr[j] = *(const bf16x8*)(sB + (wn * 64 + j * 32 + l31) * GLD + s * 16 + h * 8);
; #pragma unroll
;             for (int i = 0; i < MI; ++i)
; #pragma unroll
;                 for (int j = 0; j < 2; ++j) {
;                     if (SWAP) acc[i][j] = MFMA(bfr[j], af[i], acc[i][j]);
;                     else acc[i][j] = MFMA(af[i], bfr[j], acc[i][j]);
;                 }
;         }
;         __syncthreads();
;         if (more) {
; #pragma unroll
;             for (int i = 0; i < 2 * MI; ++i) *(u32x4*)(sA + (lr + 32 * i) * GLD + lc) = ra[i];
; #pragma unroll
;             for (int i = 0; i < 4; ++i) *(u32x4*)(sB + (lr + 32 * i) * GLD + lc) = rb[i];
;         }
;         __syncthreads();
.LBB0_689:
	ds_read_b128 v[226:229], v193 offset:36864
	ds_read_b128 v[230:233], v191
	ds_read_b128 v[234:237], v193 offset:41472
	ds_read_b128 v[218:221], v191 offset:4608
	ds_read_b128 v[214:217], v191 offset:9216
	ds_read_b128 v[210:213], v192
	ds_read_b128 v[238:241], v193 offset:36896
	ds_read_b128 v[222:225], v193 offset:41504
	s_cmpk_lt_u32 s21, 0xac0
	s_cselect_b64 s[10:11], -1, 0
	s_cmpk_gt_u32 s21, 0xabf
	s_cselect_b64 s[8:9], -1, 0
	s_and_b64 vcc, exec, s[8:9]
	s_cbranch_vccnz .LBB0_691
	s_waitcnt vmcnt(5)
	v_lshl_add_u64 v[154:155], v[186:187], 0, v[0:1]
	v_add_co_u32_e32 v130, vcc, 0xa888000, v154
	s_waitcnt vmcnt(1)
	v_lshl_add_u64 v[170:171], v[188:189], 0, v[0:1]
	v_addc_co_u32_e32 v131, vcc, 0, v155, vcc
	v_add_co_u32_e32 v134, vcc, 0xa8b4000, v154
	s_nop 1
	v_addc_co_u32_e32 v135, vcc, 0, v155, vcc
	v_add_co_u32_e32 v138, vcc, 0xa8e0000, v154
	global_load_dwordx4 v[130:133], v[130:131], off offset:128
	s_nop 0
	global_load_dwordx4 v[134:137], v[134:135], off offset:128
	v_addc_co_u32_e32 v139, vcc, 0, v155, vcc
	v_add_co_u32_e32 v142, vcc, 0xa90c000, v154
	s_nop 1
	v_addc_co_u32_e32 v143, vcc, 0, v155, vcc
	v_add_co_u32_e32 v146, vcc, 0xa938000, v154
	global_load_dwordx4 v[138:141], v[138:139], off offset:128
	s_nop 0
	global_load_dwordx4 v[142:145], v[142:143], off offset:128
	v_addc_co_u32_e32 v147, vcc, 0, v155, vcc
	v_add_co_u32_e32 v150, vcc, 0xa964000, v154
	s_nop 1
	v_addc_co_u32_e32 v151, vcc, 0, v155, vcc
	v_add_co_u32_e32 v156, vcc, 0xa990000, v154
	global_load_dwordx4 v[146:149], v[146:147], off offset:128
	s_nop 0
	global_load_dwordx4 v[150:153], v[150:151], off offset:128
	v_addc_co_u32_e32 v157, vcc, 0, v155, vcc
	v_add_co_u32_e32 v158, vcc, 0xa9bc000, v154
	s_nop 1
	v_addc_co_u32_e32 v159, vcc, 0, v155, vcc
	v_add_co_u32_e32 v162, vcc, 0x2c08000, v170
	global_load_dwordx4 v[154:157], v[156:157], off offset:128
	s_nop 0
	global_load_dwordx4 v[158:161], v[158:159], off offset:128
	v_addc_co_u32_e32 v163, vcc, 0, v171, vcc
	v_add_co_u32_e32 v166, vcc, 0x2c34000, v170
	s_nop 1
	v_addc_co_u32_e32 v167, vcc, 0, v171, vcc
	v_add_co_u32_e32 v172, vcc, 0x2c60000, v170
	global_load_dwordx4 v[162:165], v[162:163], off offset:128
	s_nop 0
	global_load_dwordx4 v[166:169], v[166:167], off offset:128
	v_addc_co_u32_e32 v173, vcc, 0, v171, vcc
	s_waitcnt vmcnt(10)
	v_add_co_u32_e32 v174, vcc, 0x2c8c000, v170
	s_nop 1
	v_addc_co_u32_e32 v175, vcc, 0, v171, vcc
	global_load_dwordx4 v[170:173], v[172:173], off offset:128
	s_nop 0
	global_load_dwordx4 v[174:177], v[174:175], off offset:128
.LBB0_691:
	s_andn2_b64 vcc, exec, s[10:11]
	s_waitcnt lgkmcnt(6)
	v_mfma_f32_32x32x16_bf16 v[114:129], v[226:229], v[230:233], v[114:129]
	s_waitcnt lgkmcnt(5)
	v_mfma_f32_32x32x16_bf16 v[98:113], v[234:237], v[230:233], v[98:113]
	ds_read_b128 v[230:233], v191 offset:32
	s_waitcnt lgkmcnt(5)
	v_mfma_f32_32x32x16_bf16 v[82:97], v[226:229], v[218:221], v[82:97]
	v_mfma_f32_32x32x16_bf16 v[66:81], v[234:237], v[218:221], v[66:81]
	ds_read_b128 v[218:221], v191 offset:4640
	s_waitcnt lgkmcnt(5)
	v_mfma_f32_32x32x16_bf16 v[50:65], v[226:229], v[214:217], v[50:65]
	v_mfma_f32_32x32x16_bf16 v[34:49], v[234:237], v[214:217], v[34:49]
	ds_read_b128 v[214:217], v191 offset:9248
	s_waitcnt lgkmcnt(5)
	v_mfma_f32_32x32x16_bf16 v[18:33], v[226:229], v[210:213], v[18:33]
	v_mfma_f32_32x32x16_bf16 v[2:17], v[234:237], v[210:213], v[2:17]
	ds_read_b128 v[210:213], v192 offset:32
	ds_read_b128 v[226:229], v193 offset:36928
	ds_read_b128 v[234:237], v193 offset:41536
	s_waitcnt lgkmcnt(5)
	v_mfma_f32_32x32x16_bf16 v[114:129], v[238:241], v[230:233], v[114:129]
	v_mfma_f32_32x32x16_bf16 v[98:113], v[222:225], v[230:233], v[98:113]
	ds_read_b128 v[230:233], v191 offset:64
	s_waitcnt lgkmcnt(5)
	v_mfma_f32_32x32x16_bf16 v[82:97], v[238:241], v[218:221], v[82:97]
	v_mfma_f32_32x32x16_bf16 v[66:81], v[222:225], v[218:221], v[66:81]
	ds_read_b128 v[218:221], v191 offset:4672
	s_waitcnt lgkmcnt(5)
	v_mfma_f32_32x32x16_bf16 v[50:65], v[238:241], v[214:217], v[50:65]
	v_mfma_f32_32x32x16_bf16 v[34:49], v[222:225], v[214:217], v[34:49]
	ds_read_b128 v[214:217], v191 offset:9280
	s_waitcnt lgkmcnt(5)
	v_mfma_f32_32x32x16_bf16 v[18:33], v[238:241], v[210:213], v[18:33]
	v_mfma_f32_32x32x16_bf16 v[2:17], v[222:225], v[210:213], v[2:17]
	ds_read_b128 v[210:213], v192 offset:64
	ds_read_b128 v[238:241], v193 offset:36960
	ds_read_b128 v[222:225], v193 offset:41568
	s_waitcnt lgkmcnt(5)
	v_mfma_f32_32x32x16_bf16 v[114:129], v[226:229], v[230:233], v[114:129]
	v_mfma_f32_32x32x16_bf16 v[98:113], v[234:237], v[230:233], v[98:113]
	ds_read_b128 v[230:233], v191 offset:96
	s_waitcnt lgkmcnt(5)
	v_mfma_f32_32x32x16_bf16 v[82:97], v[226:229], v[218:221], v[82:97]
	v_mfma_f32_32x32x16_bf16 v[66:81], v[234:237], v[218:221], v[66:81]
	ds_read_b128 v[218:221], v191 offset:4704
	s_waitcnt lgkmcnt(5)
	v_mfma_f32_32x32x16_bf16 v[50:65], v[226:229], v[214:217], v[50:65]
	v_mfma_f32_32x32x16_bf16 v[34:49], v[234:237], v[214:217], v[34:49]
	ds_read_b128 v[214:217], v191 offset:9312
	s_waitcnt lgkmcnt(5)
	v_mfma_f32_32x32x16_bf16 v[18:33], v[226:229], v[210:213], v[18:33]
	v_mfma_f32_32x32x16_bf16 v[2:17], v[234:237], v[210:213], v[2:17]
	ds_read_b128 v[210:213], v192 offset:96
	s_waitcnt lgkmcnt(3)
	v_mfma_f32_32x32x16_bf16 v[114:129], v[238:241], v[230:233], v[114:129]
	v_mfma_f32_32x32x16_bf16 v[98:113], v[222:225], v[230:233], v[98:113]
	s_waitcnt lgkmcnt(2)
	v_mfma_f32_32x32x16_bf16 v[82:97], v[238:241], v[218:221], v[82:97]
	v_mfma_f32_32x32x16_bf16 v[66:81], v[222:225], v[218:221], v[66:81]
	s_waitcnt lgkmcnt(0)
	s_barrier
	v_mfma_f32_32x32x16_bf16 v[50:65], v[238:241], v[214:217], v[50:65]
	v_mfma_f32_32x32x16_bf16 v[34:49], v[222:225], v[214:217], v[34:49]
	v_mfma_f32_32x32x16_bf16 v[18:33], v[238:241], v[210:213], v[18:33]
	v_mfma_f32_32x32x16_bf16 v[2:17], v[222:225], v[210:213], v[2:17]
	s_cbranch_vccnz .LBB0_688
	s_waitcnt vmcnt(11)
	ds_write_b128 v190, v[130:133]
	s_waitcnt vmcnt(10)
	ds_write_b128 v190, v[134:137] offset:4608
	s_waitcnt vmcnt(9)
	ds_write_b128 v190, v[138:141] offset:9216
	s_waitcnt vmcnt(8)
	ds_write_b128 v190, v[142:145] offset:13824
	s_waitcnt vmcnt(7)
	ds_write_b128 v190, v[146:149] offset:18432
	s_waitcnt vmcnt(6)
	ds_write_b128 v190, v[150:153] offset:23040
	s_waitcnt vmcnt(5)
	ds_write_b128 v190, v[154:157] offset:27648
	s_waitcnt vmcnt(4)
	ds_write_b128 v190, v[158:161] offset:32256
	s_waitcnt vmcnt(3)
	ds_write_b128 v190, v[162:165] offset:36864
	s_waitcnt vmcnt(2)
	ds_write_b128 v190, v[166:169] offset:41472
	s_waitcnt vmcnt(1)
	ds_write_b128 v190, v[170:173] offset:46080
	s_waitcnt vmcnt(0)
	ds_write_b128 v190, v[174:177] offset:50688
	s_branch .LBB0_688

; #define MFMA(a, b, c) __builtin_amdgcn_mfma_f32_32x32x16_bf16((a), (b), (c), 0, 0, 0)
; template <bool SWAP, int MI>
; DI void gemm_main(const bf16_t* __restrict__ A, int lda, const bf16_t* __restrict__ B, int ldb, int K, char* smem, f32x16 (&acc)[MI][2]) {
;     ...
;     for (int k0 = 0; k0 < K; k0 += 64) {
;         const bool more = (k0 + 64) < K;
;         if (more) {
; #pragma unroll
;             for (int i = 0; i < 2 * MI; ++i) ra[i] = *(const u32x4*)(ap + (size_t)(32 * i) * lda + k0 + 64);
; #pragma unroll
;             for (int i = 0; i < 4; ++i) rb[i] = *(const u32x4*)(bp + (size_t)(32 * i) * ldb + k0 + 64);
;         }
; #pragma unroll
;         for (int s = 0; s < 4; ++s) {
;             bf16x8 af[MI], bfr[2];
; #pragma unroll
;             for (int i = 0; i < MI; ++i) af[i] = *(const bf16x8*)(sA + (wm * (MI * 32) + i * 32 + l31) * GLD + s * 16 + h * 8);
; #pragma unroll
;             for (int j = 0; j < 2; ++j) bfr[j] = *(const bf16x8*)(sB + (wn * 64 + j * 32 + l31) * GLD + s * 16 + h * 8);
; #pragma unroll
;             for (int i = 0; i < MI; ++i)
; #pragma unroll
;                 for (int j = 0; j < 2; ++j) {
;                     if (SWAP) acc[i][j] = MFMA(bfr[j], af[i], acc[i][j]);
;                     else acc[i][j] = MFMA(af[i], bfr[j], acc[i][j]);
;                 }
;         }
;         __syncthreads();
;         if (more) {
; #pragma unroll
;             for (int i = 0; i < 2 * MI; ++i) *(u32x4*)(sA + (lr + 32 * i) * GLD + lc) = ra[i];
; #pragma unroll
;             for (int i = 0; i < 4; ++i) *(u32x4*)(sB + (lr + 32 * i) * GLD + lc) = rb[i];
;         }
;         __syncthreads();
;     }
.LBB0_707:
	ds_read_b128 v[192:195], v191 offset:36864
	ds_read_b128 v[226:229], v189
	ds_read_b128 v[230:233], v191 offset:41472
	ds_read_b128 v[222:225], v189 offset:4608
	ds_read_b128 v[218:221], v189 offset:9216
	ds_read_b128 v[214:217], v190
	ds_read_b128 v[234:237], v191 offset:36896
	ds_read_b128 v[238:241], v191 offset:41504
	s_cmpk_lt_u32 s11, 0x3c0
	s_cselect_b64 s[14:15], -1, 0
	s_cmpk_gt_u32 s11, 0x3bf
	s_cselect_b64 s[12:13], -1, 0
	s_and_b64 vcc, exec, s[12:13]
	s_cbranch_vccnz .LBB0_709
	s_waitcnt vmcnt(5)
	v_lshl_add_u64 v[154:155], v[186:187], 0, v[0:1]
	v_add_co_u32_e32 v130, vcc, 0x6888000, v154
	s_waitcnt vmcnt(1)
	v_lshl_add_u64 v[170:171], v[184:185], 0, v[0:1]
	v_addc_co_u32_e32 v131, vcc, 0, v155, vcc
	v_add_co_u32_e32 v134, vcc, 0x6898000, v154
	s_nop 1
	v_addc_co_u32_e32 v135, vcc, 0, v155, vcc
	v_add_co_u32_e32 v138, vcc, 0x68a8000, v154
	global_load_dwordx4 v[130:133], v[130:131], off offset:128
	s_nop 0
	global_load_dwordx4 v[134:137], v[134:135], off offset:128
	v_addc_co_u32_e32 v139, vcc, 0, v155, vcc
	v_add_co_u32_e32 v142, vcc, 0x68b8000, v154
	s_nop 1
	v_addc_co_u32_e32 v143, vcc, 0, v155, vcc
	v_add_co_u32_e32 v146, vcc, 0x68c8000, v154
	global_load_dwordx4 v[138:141], v[138:139], off offset:128
	s_nop 0
	global_load_dwordx4 v[142:145], v[142:143], off offset:128
	v_addc_co_u32_e32 v147, vcc, 0, v155, vcc
	v_add_co_u32_e32 v150, vcc, 0x68d8000, v154
	s_nop 1
	v_addc_co_u32_e32 v151, vcc, 0, v155, vcc
	v_add_co_u32_e32 v156, vcc, 0x68e8000, v154
	global_load_dwordx4 v[146:149], v[146:147], off offset:128
	s_nop 0
	global_load_dwordx4 v[150:153], v[150:151], off offset:128
	v_addc_co_u32_e32 v157, vcc, 0, v155, vcc
	v_add_co_u32_e32 v158, vcc, 0x68f8000, v154
	s_nop 1
	v_addc_co_u32_e32 v159, vcc, 0, v155, vcc
	v_add_co_u32_e32 v166, vcc, 0x10000, v170
	global_load_dwordx4 v[154:157], v[156:157], off offset:128
	s_nop 0
	global_load_dwordx4 v[158:161], v[158:159], off offset:128
	v_addc_co_u32_e32 v167, vcc, 0, v171, vcc
	v_add_co_u32_e32 v172, vcc, 0x20000, v170
	global_load_dwordx4 v[162:165], v[170:171], off offset:128
	s_nop 0
	global_load_dwordx4 v[166:169], v[166:167], off offset:128
	v_addc_co_u32_e32 v173, vcc, 0, v171, vcc
	s_waitcnt vmcnt(10)
	v_add_co_u32_e32 v174, vcc, 0x30000, v170
	s_nop 1
	v_addc_co_u32_e32 v175, vcc, 0, v171, vcc
	global_load_dwordx4 v[170:173], v[172:173], off offset:128
	s_nop 0
	global_load_dwordx4 v[174:177], v[174:175], off offset:128
.LBB0_709:
	s_andn2_b64 vcc, exec, s[14:15]
	s_waitcnt lgkmcnt(6)
	v_mfma_f32_32x32x16_bf16 v[114:129], v[192:195], v[226:229], v[114:129]
	s_waitcnt lgkmcnt(5)
	v_mfma_f32_32x32x16_bf16 v[98:113], v[230:233], v[226:229], v[98:113]
	ds_read_b128 v[226:229], v189 offset:32
	s_waitcnt lgkmcnt(5)
	v_mfma_f32_32x32x16_bf16 v[82:97], v[192:195], v[222:225], v[82:97]
	v_mfma_f32_32x32x16_bf16 v[66:81], v[230:233], v[222:225], v[66:81]
	ds_read_b128 v[222:225], v189 offset:4640
	s_waitcnt lgkmcnt(5)
	v_mfma_f32_32x32x16_bf16 v[50:65], v[192:195], v[218:221], v[50:65]
	v_mfma_f32_32x32x16_bf16 v[34:49], v[230:233], v[218:221], v[34:49]
	ds_read_b128 v[218:221], v189 offset:9248
	s_waitcnt lgkmcnt(5)
	v_mfma_f32_32x32x16_bf16 v[18:33], v[192:195], v[214:217], v[18:33]
	v_mfma_f32_32x32x16_bf16 v[2:17], v[230:233], v[214:217], v[2:17]
	ds_read_b128 v[214:217], v190 offset:32
	ds_read_b128 v[192:195], v191 offset:36928
	ds_read_b128 v[230:233], v191 offset:41536
	s_waitcnt lgkmcnt(5)
	v_mfma_f32_32x32x16_bf16 v[114:129], v[234:237], v[226:229], v[114:129]
	v_mfma_f32_32x32x16_bf16 v[98:113], v[238:241], v[226:229], v[98:113]
	ds_read_b128 v[226:229], v189 offset:64
	s_waitcnt lgkmcnt(5)
	v_mfma_f32_32x32x16_bf16 v[82:97], v[234:237], v[222:225], v[82:97]
	v_mfma_f32_32x32x16_bf16 v[66:81], v[238:241], v[222:225], v[66:81]
	ds_read_b128 v[222:225], v189 offset:4672
	s_waitcnt lgkmcnt(5)
	v_mfma_f32_32x32x16_bf16 v[50:65], v[234:237], v[218:221], v[50:65]
	v_mfma_f32_32x32x16_bf16 v[34:49], v[238:241], v[218:221], v[34:49]
	ds_read_b128 v[218:221], v189 offset:9280
	s_waitcnt lgkmcnt(5)
	v_mfma_f32_32x32x16_bf16 v[18:33], v[234:237], v[214:217], v[18:33]
	v_mfma_f32_32x32x16_bf16 v[2:17], v[238:241], v[214:217], v[2:17]
	ds_read_b128 v[214:217], v190 offset:64
	ds_read_b128 v[234:237], v191 offset:36960
	ds_read_b128 v[238:241], v191 offset:41568
	s_waitcnt lgkmcnt(5)
	v_mfma_f32_32x32x16_bf16 v[114:129], v[192:195], v[226:229], v[114:129]
	v_mfma_f32_32x32x16_bf16 v[98:113], v[230:233], v[226:229], v[98:113]
	ds_read_b128 v[226:229], v189 offset:96
	s_waitcnt lgkmcnt(5)
	v_mfma_f32_32x32x16_bf16 v[82:97], v[192:195], v[222:225], v[82:97]
	v_mfma_f32_32x32x16_bf16 v[66:81], v[230:233], v[222:225], v[66:81]
	ds_read_b128 v[222:225], v189 offset:4704
	s_waitcnt lgkmcnt(5)
	v_mfma_f32_32x32x16_bf16 v[50:65], v[192:195], v[218:221], v[50:65]
	v_mfma_f32_32x32x16_bf16 v[34:49], v[230:233], v[218:221], v[34:49]
	ds_read_b128 v[218:221], v189 offset:9312
	s_waitcnt lgkmcnt(5)
	v_mfma_f32_32x32x16_bf16 v[18:33], v[192:195], v[214:217], v[18:33]
	v_mfma_f32_32x32x16_bf16 v[2:17], v[230:233], v[214:217], v[2:17]
	ds_read_b128 v[214:217], v190 offset:96
	s_waitcnt lgkmcnt(3)
	v_mfma_f32_32x32x16_bf16 v[114:129], v[234:237], v[226:229], v[114:129]
	v_mfma_f32_32x32x16_bf16 v[98:113], v[238:241], v[226:229], v[98:113]
	s_waitcnt lgkmcnt(2)
	v_mfma_f32_32x32x16_bf16 v[82:97], v[234:237], v[222:225], v[82:97]
	v_mfma_f32_32x32x16_bf16 v[66:81], v[238:241], v[222:225], v[66:81]
	s_waitcnt lgkmcnt(0)
	s_barrier
	v_mfma_f32_32x32x16_bf16 v[50:65], v[234:237], v[218:221], v[50:65]
	v_mfma_f32_32x32x16_bf16 v[34:49], v[238:241], v[218:221], v[34:49]
	v_mfma_f32_32x32x16_bf16 v[18:33], v[234:237], v[214:217], v[18:33]
	v_mfma_f32_32x32x16_bf16 v[2:17], v[238:241], v[214:217], v[2:17]
	s_cbranch_vccnz .LBB0_706
	s_waitcnt vmcnt(11)
	ds_write_b128 v188, v[130:133]
	s_waitcnt vmcnt(10)
	ds_write_b128 v188, v[134:137] offset:4608
	s_waitcnt vmcnt(9)
	ds_write_b128 v188, v[138:141] offset:9216
	s_waitcnt vmcnt(8)
	ds_write_b128 v188, v[142:145] offset:13824
	s_waitcnt vmcnt(7)
	ds_write_b128 v188, v[146:149] offset:18432
	s_waitcnt vmcnt(6)
	ds_write_b128 v188, v[150:153] offset:23040
	s_waitcnt vmcnt(5)
	ds_write_b128 v188, v[154:157] offset:27648
	s_waitcnt vmcnt(4)
	ds_write_b128 v188, v[158:161] offset:32256
	s_waitcnt vmcnt(3)
	ds_write_b128 v188, v[162:165] offset:36864
	s_waitcnt vmcnt(2)
	ds_write_b128 v188, v[166:169] offset:41472
	s_waitcnt vmcnt(1)
	ds_write_b128 v188, v[170:173] offset:46080
	s_waitcnt vmcnt(0)
	ds_write_b128 v188, v[174:177] offset:50688
	s_branch .LBB0_706

; #define MFMA(a, b, c) __builtin_amdgcn_mfma_f32_32x32x16_bf16((a), (b), (c), 0, 0, 0)
; template <bool SWAP, int MI>
; DI void gemm_main(const bf16_t* __restrict__ A, int lda, const bf16_t* __restrict__ B, int ldb, int K, char* smem, f32x16 (&acc)[MI][2]) {
;     ...
;     for (int k0 = 0; k0 < K; k0 += 64) {
;         const bool more = (k0 + 64) < K;
;         if (more) {
; #pragma unroll
;             for (int i = 0; i < 2 * MI; ++i) ra[i] = *(const u32x4*)(ap + (size_t)(32 * i) * lda + k0 + 64);
; #pragma unroll
;             for (int i = 0; i < 4; ++i) rb[i] = *(const u32x4*)(bp + (size_t)(32 * i) * ldb + k0 + 64);
;         }
; #pragma unroll
;         for (int s = 0; s < 4; ++s) {
;             bf16x8 af[MI], bfr[2];
; #pragma unroll
;             for (int i = 0; i < MI; ++i) af[i] = *(const bf16x8*)(sA + (wm * (MI * 32) + i * 32 + l31) * GLD + s * 16 + h * 8);
; #pragma unroll
;             for (int j = 0; j < 2; ++j) bfr[j] = *(const bf16x8*)(sB + (wn * 64 + j * 32 + l31) * GLD + s * 16 + h * 8);
; #pragma unroll
;             for (int i = 0; i < MI; ++i)
; #pragma unroll
;                 for (int j = 0; j < 2; ++j) {
;                     if (SWAP) acc[i][j] = MFMA(bfr[j], af[i], acc[i][j]);
;                     else acc[i][j] = MFMA(af[i], bfr[j], acc[i][j]);
;                 }
;         }
;         __syncthreads();
;         if (more) {
; #pragma unroll
;             for (int i = 0; i < 2 * MI; ++i) *(u32x4*)(sA + (lr + 32 * i) * GLD + lc) = ra[i];
; #pragma unroll
;             for (int i = 0; i < 4; ++i) *(u32x4*)(sB + (lr + 32 * i) * GLD + lc) = rb[i];
;         }
;         __syncthreads();
;     }
.LBB0_1723:
	ds_read_b128 v[186:189], v185 offset:36864
	ds_read_b128 v[190:193], v183
	ds_read_b128 v[226:229], v185 offset:41472
	ds_read_b128 v[238:241], v183 offset:4608
	ds_read_b128 v[222:225], v183 offset:9216
	ds_read_b128 v[218:221], v184
	ds_read_b128 v[230:233], v185 offset:36896
	ds_read_b128 v[234:237], v185 offset:41504
	s_cmpk_lt_u32 s9, 0x3c0
	s_cselect_b64 s[12:13], -1, 0
	s_cmpk_gt_u32 s9, 0x3bf
	s_cselect_b64 s[0:1], -1, 0
	s_and_b64 vcc, exec, s[0:1]
	s_cbranch_vccnz .LBB0_1725
	s_waitcnt vmcnt(5)
	v_lshl_add_u64 v[154:155], v[178:179], 0, v[0:1]
	v_add_co_u32_e32 v130, vcc, 0x4000000, v154
	s_waitcnt vmcnt(1)
	v_lshl_add_u64 v[170:171], v[180:181], 0, v[0:1]
	v_addc_co_u32_e32 v131, vcc, 0, v155, vcc
	v_add_co_u32_e32 v134, vcc, 0x4010000, v154
	s_nop 1
	v_addc_co_u32_e32 v135, vcc, 0, v155, vcc
	v_add_co_u32_e32 v138, vcc, 0x4020000, v154
	global_load_dwordx4 v[130:133], v[130:131], off offset:128
	s_nop 0
	global_load_dwordx4 v[134:137], v[134:135], off offset:128
	v_addc_co_u32_e32 v139, vcc, 0, v155, vcc
	v_add_co_u32_e32 v142, vcc, 0x4030000, v154
	s_nop 1
	v_addc_co_u32_e32 v143, vcc, 0, v155, vcc
	v_add_co_u32_e32 v146, vcc, 0x4040000, v154
	global_load_dwordx4 v[138:141], v[138:139], off offset:128
	s_nop 0
	global_load_dwordx4 v[142:145], v[142:143], off offset:128
	v_addc_co_u32_e32 v147, vcc, 0, v155, vcc
	v_add_co_u32_e32 v150, vcc, 0x4050000, v154
	s_nop 1
	v_addc_co_u32_e32 v151, vcc, 0, v155, vcc
	v_add_co_u32_e32 v156, vcc, 0x4060000, v154
	global_load_dwordx4 v[146:149], v[146:147], off offset:128
	s_nop 0
	global_load_dwordx4 v[150:153], v[150:151], off offset:128
	v_addc_co_u32_e32 v157, vcc, 0, v155, vcc
	v_add_co_u32_e32 v158, vcc, 0x4070000, v154
	s_nop 1
	v_addc_co_u32_e32 v159, vcc, 0, v155, vcc
	v_add_co_u32_e32 v162, vcc, 0x4208000, v170
	global_load_dwordx4 v[154:157], v[156:157], off offset:128
	s_nop 0
	global_load_dwordx4 v[158:161], v[158:159], off offset:128
	v_addc_co_u32_e32 v163, vcc, 0, v171, vcc
	v_add_co_u32_e32 v166, vcc, 0x4218000, v170
	s_nop 1
	v_addc_co_u32_e32 v167, vcc, 0, v171, vcc
	v_add_co_u32_e32 v172, vcc, 0x4228000, v170
	global_load_dwordx4 v[162:165], v[162:163], off offset:128
	s_nop 0
	global_load_dwordx4 v[166:169], v[166:167], off offset:128
	v_addc_co_u32_e32 v173, vcc, 0, v171, vcc
	s_waitcnt vmcnt(10)
	v_add_co_u32_e32 v174, vcc, 0x4238000, v170
	s_nop 1
	v_addc_co_u32_e32 v175, vcc, 0, v171, vcc
	global_load_dwordx4 v[170:173], v[172:173], off offset:128
	s_nop 0
	global_load_dwordx4 v[174:177], v[174:175], off offset:128
.LBB0_1725:
	s_andn2_b64 vcc, exec, s[12:13]
	s_waitcnt lgkmcnt(6)
	v_mfma_f32_32x32x16_bf16 v[114:129], v[186:189], v[190:193], v[114:129]
	s_waitcnt lgkmcnt(5)
	v_mfma_f32_32x32x16_bf16 v[98:113], v[226:229], v[190:193], v[98:113]
	ds_read_b128 v[190:193], v183 offset:32
	s_waitcnt lgkmcnt(5)
	v_mfma_f32_32x32x16_bf16 v[82:97], v[186:189], v[238:241], v[82:97]
	v_mfma_f32_32x32x16_bf16 v[66:81], v[226:229], v[238:241], v[66:81]
	ds_read_b128 v[238:241], v183 offset:4640
	s_waitcnt lgkmcnt(5)
	v_mfma_f32_32x32x16_bf16 v[50:65], v[186:189], v[222:225], v[50:65]
	v_mfma_f32_32x32x16_bf16 v[34:49], v[226:229], v[222:225], v[34:49]
	ds_read_b128 v[222:225], v183 offset:9248
	s_waitcnt lgkmcnt(5)
	v_mfma_f32_32x32x16_bf16 v[18:33], v[186:189], v[218:221], v[18:33]
	v_mfma_f32_32x32x16_bf16 v[2:17], v[226:229], v[218:221], v[2:17]
	ds_read_b128 v[218:221], v184 offset:32
	ds_read_b128 v[186:189], v185 offset:36928
	ds_read_b128 v[226:229], v185 offset:41536
	s_waitcnt lgkmcnt(5)
	v_mfma_f32_32x32x16_bf16 v[114:129], v[230:233], v[190:193], v[114:129]
	v_mfma_f32_32x32x16_bf16 v[98:113], v[234:237], v[190:193], v[98:113]
	ds_read_b128 v[190:193], v183 offset:64
	s_waitcnt lgkmcnt(5)
	v_mfma_f32_32x32x16_bf16 v[82:97], v[230:233], v[238:241], v[82:97]
	v_mfma_f32_32x32x16_bf16 v[66:81], v[234:237], v[238:241], v[66:81]
	ds_read_b128 v[238:241], v183 offset:4672
	s_waitcnt lgkmcnt(5)
	v_mfma_f32_32x32x16_bf16 v[50:65], v[230:233], v[222:225], v[50:65]
	v_mfma_f32_32x32x16_bf16 v[34:49], v[234:237], v[222:225], v[34:49]
	ds_read_b128 v[222:225], v183 offset:9280
	s_waitcnt lgkmcnt(5)
	v_mfma_f32_32x32x16_bf16 v[18:33], v[230:233], v[218:221], v[18:33]
	v_mfma_f32_32x32x16_bf16 v[2:17], v[234:237], v[218:221], v[2:17]
	ds_read_b128 v[218:221], v184 offset:64
	ds_read_b128 v[230:233], v185 offset:36960
	ds_read_b128 v[234:237], v185 offset:41568
	s_waitcnt lgkmcnt(5)
	v_mfma_f32_32x32x16_bf16 v[114:129], v[186:189], v[190:193], v[114:129]
	v_mfma_f32_32x32x16_bf16 v[98:113], v[226:229], v[190:193], v[98:113]
	ds_read_b128 v[190:193], v183 offset:96
	s_waitcnt lgkmcnt(5)
	v_mfma_f32_32x32x16_bf16 v[82:97], v[186:189], v[238:241], v[82:97]
	v_mfma_f32_32x32x16_bf16 v[66:81], v[226:229], v[238:241], v[66:81]
	ds_read_b128 v[238:241], v183 offset:4704
	s_waitcnt lgkmcnt(5)
	v_mfma_f32_32x32x16_bf16 v[50:65], v[186:189], v[222:225], v[50:65]
	v_mfma_f32_32x32x16_bf16 v[34:49], v[226:229], v[222:225], v[34:49]
	ds_read_b128 v[222:225], v183 offset:9312
	s_waitcnt lgkmcnt(5)
	v_mfma_f32_32x32x16_bf16 v[18:33], v[186:189], v[218:221], v[18:33]
	v_mfma_f32_32x32x16_bf16 v[2:17], v[226:229], v[218:221], v[2:17]
	ds_read_b128 v[218:221], v184 offset:96
	s_waitcnt lgkmcnt(3)
	v_mfma_f32_32x32x16_bf16 v[114:129], v[230:233], v[190:193], v[114:129]
	v_mfma_f32_32x32x16_bf16 v[98:113], v[234:237], v[190:193], v[98:113]
	s_waitcnt lgkmcnt(2)
	v_mfma_f32_32x32x16_bf16 v[82:97], v[230:233], v[238:241], v[82:97]
	v_mfma_f32_32x32x16_bf16 v[66:81], v[234:237], v[238:241], v[66:81]
	s_waitcnt lgkmcnt(0)
	s_barrier
	v_mfma_f32_32x32x16_bf16 v[50:65], v[230:233], v[222:225], v[50:65]
	v_mfma_f32_32x32x16_bf16 v[34:49], v[234:237], v[222:225], v[34:49]
	v_mfma_f32_32x32x16_bf16 v[18:33], v[230:233], v[218:221], v[18:33]
	v_mfma_f32_32x32x16_bf16 v[2:17], v[234:237], v[218:221], v[2:17]
	s_cbranch_vccnz .LBB0_1722
	s_waitcnt vmcnt(11)
	ds_write_b128 v182, v[130:133]
	s_waitcnt vmcnt(10)
	ds_write_b128 v182, v[134:137] offset:4608
	s_waitcnt vmcnt(9)
	ds_write_b128 v182, v[138:141] offset:9216
	s_waitcnt vmcnt(8)
	ds_write_b128 v182, v[142:145] offset:13824
	s_waitcnt vmcnt(7)
	ds_write_b128 v182, v[146:149] offset:18432
	s_waitcnt vmcnt(6)
	ds_write_b128 v182, v[150:153] offset:23040
	s_waitcnt vmcnt(5)
	ds_write_b128 v182, v[154:157] offset:27648
	s_waitcnt vmcnt(4)
	ds_write_b128 v182, v[158:161] offset:32256
	s_waitcnt vmcnt(3)
	ds_write_b128 v182, v[162:165] offset:36864
	s_waitcnt vmcnt(2)
	ds_write_b128 v182, v[166:169] offset:41472
	s_waitcnt vmcnt(1)
	ds_write_b128 v182, v[170:173] offset:46080
	s_waitcnt vmcnt(0)
	ds_write_b128 v182, v[174:177] offset:50688
	s_branch .LBB0_1722

; #define MFMA(a, b, c) __builtin_amdgcn_mfma_f32_32x32x16_bf16((a), (b), (c), 0, 0, 0)
; template <bool SWAP, int MI>
; DI void gemm_main(const bf16_t* __restrict__ A, int lda, const bf16_t* __restrict__ B, int ldb, int K, char* smem, f32x16 (&acc)[MI][2]) {
;     ...
;     for (int k0 = 0; k0 < K; k0 += 64) {
;         const bool more = (k0 + 64) < K;
;         if (more) {
; #pragma unroll
;             for (int i = 0; i < 2 * MI; ++i) ra[i] = *(const u32x4*)(ap + (size_t)(32 * i) * lda + k0 + 64);
; #pragma unroll
;             for (int i = 0; i < 4; ++i) rb[i] = *(const u32x4*)(bp + (size_t)(32 * i) * ldb + k0 + 64);
;         }
; #pragma unroll
;         for (int s = 0; s < 4; ++s) {
;             bf16x8 af[MI], bfr[2];
; #pragma unroll
;             for (int i = 0; i < MI; ++i) af[i] = *(const bf16x8*)(sA + (wm * (MI * 32) + i * 32 + l31) * GLD + s * 16 + h * 8);
; #pragma unroll
;             for (int j = 0; j < 2; ++j) bfr[j] = *(const bf16x8*)(sB + (wn * 64 + j * 32 + l31) * GLD + s * 16 + h * 8);
; #pragma unroll
;             for (int i = 0; i < MI; ++i)
; #pragma unroll
;                 for (int j = 0; j < 2; ++j) {
;                     if (SWAP) acc[i][j] = MFMA(bfr[j], af[i], acc[i][j]);
;                     else acc[i][j] = MFMA(af[i], bfr[j], acc[i][j]);
;                 }
;         }
;         __syncthreads();
;         if (more) {
; #pragma unroll
;             for (int i = 0; i < 2 * MI; ++i) *(u32x4*)(sA + (lr + 32 * i) * GLD + lc) = ra[i];
; #pragma unroll
;             for (int i = 0; i < 4; ++i) *(u32x4*)(sB + (lr + 32 * i) * GLD + lc) = rb[i];
;         }
;         __syncthreads();
;     }
.LBB0_1739:
	ds_read_b128 v[190:193], v185 offset:36864
	ds_read_b128 v[186:189], v183
	ds_read_b128 v[226:229], v185 offset:41472
	ds_read_b128 v[238:241], v183 offset:4608
	ds_read_b128 v[222:225], v183 offset:9216
	ds_read_b128 v[218:221], v184
	ds_read_b128 v[230:233], v185 offset:36896
	ds_read_b128 v[234:237], v185 offset:41504
	s_cmpk_lt_u32 s9, 0x3c0
	s_cselect_b64 s[12:13], -1, 0
	s_cmpk_gt_u32 s9, 0x3bf
	s_cselect_b64 s[0:1], -1, 0
	s_and_b64 vcc, exec, s[0:1]
	s_cbranch_vccnz .LBB0_1741
	s_waitcnt vmcnt(5)
	v_lshl_add_u64 v[154:155], v[178:179], 0, v[0:1]
	v_add_co_u32_e32 v130, vcc, 0x4000000, v154
	s_waitcnt vmcnt(1)
	v_lshl_add_u64 v[170:171], v[180:181], 0, v[0:1]
	v_addc_co_u32_e32 v131, vcc, 0, v155, vcc
	v_add_co_u32_e32 v134, vcc, 0x4010000, v154
	s_nop 1
	v_addc_co_u32_e32 v135, vcc, 0, v155, vcc
	v_add_co_u32_e32 v138, vcc, 0x4020000, v154
	global_load_dwordx4 v[130:133], v[130:131], off offset:128
	s_nop 0
	global_load_dwordx4 v[134:137], v[134:135], off offset:128
	v_addc_co_u32_e32 v139, vcc, 0, v155, vcc
	v_add_co_u32_e32 v142, vcc, 0x4030000, v154
	s_nop 1
	v_addc_co_u32_e32 v143, vcc, 0, v155, vcc
	v_add_co_u32_e32 v146, vcc, 0x4040000, v154
	global_load_dwordx4 v[138:141], v[138:139], off offset:128
	s_nop 0
	global_load_dwordx4 v[142:145], v[142:143], off offset:128
	v_addc_co_u32_e32 v147, vcc, 0, v155, vcc
	v_add_co_u32_e32 v150, vcc, 0x4050000, v154
	s_nop 1
	v_addc_co_u32_e32 v151, vcc, 0, v155, vcc
	v_add_co_u32_e32 v156, vcc, 0x4060000, v154
	global_load_dwordx4 v[146:149], v[146:147], off offset:128
	s_nop 0
	global_load_dwordx4 v[150:153], v[150:151], off offset:128
	v_addc_co_u32_e32 v157, vcc, 0, v155, vcc
	v_add_co_u32_e32 v158, vcc, 0x4070000, v154
	s_nop 1
	v_addc_co_u32_e32 v159, vcc, 0, v155, vcc
	v_add_co_u32_e32 v162, vcc, 0x4208000, v170
	global_load_dwordx4 v[154:157], v[156:157], off offset:128
	s_nop 0
	global_load_dwordx4 v[158:161], v[158:159], off offset:128
	v_addc_co_u32_e32 v163, vcc, 0, v171, vcc
	v_add_co_u32_e32 v166, vcc, 0x4218000, v170
	s_nop 1
	v_addc_co_u32_e32 v167, vcc, 0, v171, vcc
	v_add_co_u32_e32 v172, vcc, 0x4228000, v170
	global_load_dwordx4 v[162:165], v[162:163], off offset:128
	s_nop 0
	global_load_dwordx4 v[166:169], v[166:167], off offset:128
	v_addc_co_u32_e32 v173, vcc, 0, v171, vcc
	s_waitcnt vmcnt(10)
	v_add_co_u32_e32 v174, vcc, 0x4238000, v170
	s_nop 1
	v_addc_co_u32_e32 v175, vcc, 0, v171, vcc
	global_load_dwordx4 v[170:173], v[172:173], off offset:128
	s_nop 0
	global_load_dwordx4 v[174:177], v[174:175], off offset:128
.LBB0_1741:
	s_andn2_b64 vcc, exec, s[12:13]
	s_waitcnt lgkmcnt(6)
	v_mfma_f32_32x32x16_bf16 v[114:129], v[186:189], v[190:193], v[114:129]
	s_waitcnt lgkmcnt(5)
	v_mfma_f32_32x32x16_bf16 v[50:65], v[186:189], v[226:229], v[50:65]
	ds_read_b128 v[186:189], v183 offset:32
	s_waitcnt lgkmcnt(5)
	v_mfma_f32_32x32x16_bf16 v[98:113], v[238:241], v[190:193], v[98:113]
	v_mfma_f32_32x32x16_bf16 v[34:49], v[238:241], v[226:229], v[34:49]
	ds_read_b128 v[238:241], v183 offset:4640
	s_waitcnt lgkmcnt(5)
	v_mfma_f32_32x32x16_bf16 v[82:97], v[222:225], v[190:193], v[82:97]
	v_mfma_f32_32x32x16_bf16 v[18:33], v[222:225], v[226:229], v[18:33]
	ds_read_b128 v[222:225], v183 offset:9248
	s_waitcnt lgkmcnt(5)
	v_mfma_f32_32x32x16_bf16 v[66:81], v[218:221], v[190:193], v[66:81]
	v_mfma_f32_32x32x16_bf16 v[2:17], v[218:221], v[226:229], v[2:17]
	ds_read_b128 v[218:221], v184 offset:32
	ds_read_b128 v[190:193], v185 offset:36928
	ds_read_b128 v[226:229], v185 offset:41536
	s_waitcnt lgkmcnt(5)
	v_mfma_f32_32x32x16_bf16 v[114:129], v[186:189], v[230:233], v[114:129]
	v_mfma_f32_32x32x16_bf16 v[50:65], v[186:189], v[234:237], v[50:65]
	ds_read_b128 v[186:189], v183 offset:64
	s_waitcnt lgkmcnt(5)
	v_mfma_f32_32x32x16_bf16 v[98:113], v[238:241], v[230:233], v[98:113]
	v_mfma_f32_32x32x16_bf16 v[34:49], v[238:241], v[234:237], v[34:49]
	ds_read_b128 v[238:241], v183 offset:4672
	s_waitcnt lgkmcnt(5)
	v_mfma_f32_32x32x16_bf16 v[82:97], v[222:225], v[230:233], v[82:97]
	v_mfma_f32_32x32x16_bf16 v[18:33], v[222:225], v[234:237], v[18:33]
	ds_read_b128 v[222:225], v183 offset:9280
	s_waitcnt lgkmcnt(5)
	v_mfma_f32_32x32x16_bf16 v[66:81], v[218:221], v[230:233], v[66:81]
	v_mfma_f32_32x32x16_bf16 v[2:17], v[218:221], v[234:237], v[2:17]
	ds_read_b128 v[218:221], v184 offset:64
	ds_read_b128 v[230:233], v185 offset:36960
	ds_read_b128 v[234:237], v185 offset:41568
	s_waitcnt lgkmcnt(5)
	v_mfma_f32_32x32x16_bf16 v[114:129], v[186:189], v[190:193], v[114:129]
	v_mfma_f32_32x32x16_bf16 v[50:65], v[186:189], v[226:229], v[50:65]
	ds_read_b128 v[186:189], v183 offset:96
	s_waitcnt lgkmcnt(5)
	v_mfma_f32_32x32x16_bf16 v[98:113], v[238:241], v[190:193], v[98:113]
	v_mfma_f32_32x32x16_bf16 v[34:49], v[238:241], v[226:229], v[34:49]
	ds_read_b128 v[238:241], v183 offset:4704
	s_waitcnt lgkmcnt(5)
	v_mfma_f32_32x32x16_bf16 v[82:97], v[222:225], v[190:193], v[82:97]
	v_mfma_f32_32x32x16_bf16 v[18:33], v[222:225], v[226:229], v[18:33]
	ds_read_b128 v[222:225], v183 offset:9312
	s_waitcnt lgkmcnt(5)
	v_mfma_f32_32x32x16_bf16 v[66:81], v[218:221], v[190:193], v[66:81]
	v_mfma_f32_32x32x16_bf16 v[2:17], v[218:221], v[226:229], v[2:17]
	ds_read_b128 v[218:221], v184 offset:96
	s_waitcnt lgkmcnt(3)
	v_mfma_f32_32x32x16_bf16 v[114:129], v[186:189], v[230:233], v[114:129]
	v_mfma_f32_32x32x16_bf16 v[50:65], v[186:189], v[234:237], v[50:65]
	s_waitcnt lgkmcnt(2)
	v_mfma_f32_32x32x16_bf16 v[98:113], v[238:241], v[230:233], v[98:113]
	v_mfma_f32_32x32x16_bf16 v[34:49], v[238:241], v[234:237], v[34:49]
	s_waitcnt lgkmcnt(0)
	s_barrier
	v_mfma_f32_32x32x16_bf16 v[82:97], v[222:225], v[230:233], v[82:97]
	v_mfma_f32_32x32x16_bf16 v[18:33], v[222:225], v[234:237], v[18:33]
	v_mfma_f32_32x32x16_bf16 v[66:81], v[218:221], v[230:233], v[66:81]
	v_mfma_f32_32x32x16_bf16 v[2:17], v[218:221], v[234:237], v[2:17]
	s_cbranch_vccnz .LBB0_1738
	s_waitcnt vmcnt(11)
	ds_write_b128 v182, v[130:133]
	s_waitcnt vmcnt(10)
	ds_write_b128 v182, v[134:137] offset:4608
	s_waitcnt vmcnt(9)
	ds_write_b128 v182, v[138:141] offset:9216
	s_waitcnt vmcnt(8)
	ds_write_b128 v182, v[142:145] offset:13824
	s_waitcnt vmcnt(7)
	ds_write_b128 v182, v[146:149] offset:18432
	s_waitcnt vmcnt(6)
	ds_write_b128 v182, v[150:153] offset:23040
	s_waitcnt vmcnt(5)
	ds_write_b128 v182, v[154:157] offset:27648
	s_waitcnt vmcnt(4)
	ds_write_b128 v182, v[158:161] offset:32256
	s_waitcnt vmcnt(3)
	ds_write_b128 v182, v[162:165] offset:36864
	s_waitcnt vmcnt(2)
	ds_write_b128 v182, v[166:169] offset:41472
	s_waitcnt vmcnt(1)
	ds_write_b128 v182, v[170:173] offset:46080
	s_waitcnt vmcnt(0)
	ds_write_b128 v182, v[174:177] offset:50688
	s_branch .LBB0_1738
